# v22 plus hgrn out and hgrn local chains pipelined over state row groups
# speedup vs baseline: 1.0199x; 1.0199x over previous
; #define LAS __attribute__((address_space(3)))
; template <bool OUT> __device__ __forceinline__ void hgrn_pair(const PA& a, LAS unsigned char* lds, int layer, int bh, int s, int wave, int lane) {
;     ...
; #pragma unroll 1
;     for (int step = 0; step < 4; ++step) {
;         if (wl == step) {
; #pragma unroll
;             for (int mt = 0; mt < 4; ++mt) { const f32x4 Dp = *(const LAS f32x4*)(DLs + 16 * mt + 4 * q) * *(const LAS f32x4*)(DLs + 64 + 16 * mt + 4 * q);
; #pragma unroll
;                 for (int nt = 0; nt < 4; ++nt) {
;                     Sin[mt][nt] = *(const LAS f32x4*)(SBUF + ((mt * 4 + nt) * 64 + lane) * 4);
;                     Up[mt][nt] = Dp * Sin[mt][nt] + Up[mt][nt];
;                     *(LAS f32x4*)(SBUF + ((mt * 4 + nt) * 64 + lane) * 4) = Up[mt][nt];
;                 } }
;         }
;         __syncthreads();
;     }
.LBB0_497:
	s_add_i32 s44, s44, 1
	s_cmp_eq_u32 s44, 7
	s_waitcnt lgkmcnt(0)
	s_barrier
	s_cbranch_scc1 .LBB0_500
.LBB0_498:
	s_sub_i32 s0, s44, s8
	s_cmp_gt_u32 s0, 3
	s_cbranch_scc1 .LBB0_497
	s_cmp_eq_u32 s0, 0
	s_cbranch_scc1 .Lmy_hlc_g0
	s_cmp_eq_u32 s0, 1
	s_cbranch_scc1 .Lmy_hlc_g1
	s_cmp_eq_u32 s0, 2
	s_cbranch_scc1 .Lmy_hlc_g2
	ds_read_b128 v[66:69], v64 offset:11712
	ds_read_b128 v[70:73], v64 offset:11968
	ds_read_b128 v[74:77], v65 offset:12288
	ds_read_b128 v[78:81], v65 offset:13312
	ds_read_b128 v[82:85], v65 offset:14336
	ds_read_b128 v[86:89], v65 offset:15360
	s_waitcnt lgkmcnt(4)
	v_pk_mul_f32 v[72:73], v[68:69], v[72:73]
	v_pk_mul_f32 v[70:71], v[66:67], v[70:71]
	s_waitcnt lgkmcnt(0)
	v_pk_fma_f32 v[14:15], v[72:73], v[76:77], v[14:15]
	v_pk_fma_f32 v[12:13], v[70:71], v[74:75], v[12:13]
	v_pk_fma_f32 v[10:11], v[72:73], v[80:81], v[10:11]
	v_pk_fma_f32 v[8:9], v[70:71], v[78:79], v[8:9]
	v_pk_fma_f32 v[6:7], v[72:73], v[84:85], v[6:7]
	v_pk_fma_f32 v[4:5], v[70:71], v[82:83], v[4:5]
	v_pk_fma_f32 v[2:3], v[72:73], v[88:89], v[2:3]
	v_pk_fma_f32 v[0:1], v[70:71], v[86:87], v[0:1]
	ds_write_b128 v65, v[12:15] offset:12288
	ds_write_b128 v65, v[8:11] offset:13312
	ds_write_b128 v65, v[4:7] offset:14336
	ds_write_b128 v65, v[0:3] offset:15360
	s_branch .LBB0_497
.Lmy_hlc_g0:
	ds_read_b128 v[66:69], v64 offset:11520
	ds_read_b128 v[70:73], v64 offset:11776
	ds_read_b128 v[74:77], v65
	ds_read_b128 v[78:81], v65 offset:1024
	ds_read_b128 v[82:85], v65 offset:2048
	ds_read_b128 v[86:89], v65 offset:3072
	s_waitcnt lgkmcnt(4)
	v_pk_mul_f32 v[72:73], v[68:69], v[72:73]
	v_pk_mul_f32 v[70:71], v[66:67], v[70:71]
	s_waitcnt lgkmcnt(0)
	v_pk_fma_f32 v[62:63], v[72:73], v[76:77], v[62:63]
	v_pk_fma_f32 v[60:61], v[70:71], v[74:75], v[60:61]
	v_pk_fma_f32 v[58:59], v[72:73], v[80:81], v[58:59]
	v_pk_fma_f32 v[56:57], v[70:71], v[78:79], v[56:57]
	v_pk_fma_f32 v[54:55], v[72:73], v[84:85], v[54:55]
	v_pk_fma_f32 v[52:53], v[70:71], v[82:83], v[52:53]
	v_pk_fma_f32 v[50:51], v[72:73], v[88:89], v[50:51]
	v_pk_fma_f32 v[48:49], v[70:71], v[86:87], v[48:49]
	ds_write_b128 v65, v[60:63]
	ds_write_b128 v65, v[56:59] offset:1024
	ds_write_b128 v65, v[52:55] offset:2048
	ds_write_b128 v65, v[48:51] offset:3072
	s_branch .LBB0_497
.Lmy_hlc_g1:
	ds_read_b128 v[66:69], v64 offset:11584
	ds_read_b128 v[70:73], v64 offset:11840
	ds_read_b128 v[74:77], v65 offset:4096
	ds_read_b128 v[78:81], v65 offset:5120
	ds_read_b128 v[82:85], v65 offset:6144
	ds_read_b128 v[86:89], v65 offset:7168
	s_waitcnt lgkmcnt(4)
	v_pk_mul_f32 v[72:73], v[68:69], v[72:73]
	v_pk_mul_f32 v[70:71], v[66:67], v[70:71]
	s_waitcnt lgkmcnt(0)
	v_pk_fma_f32 v[46:47], v[72:73], v[76:77], v[46:47]
	v_pk_fma_f32 v[44:45], v[70:71], v[74:75], v[44:45]
	v_pk_fma_f32 v[42:43], v[72:73], v[80:81], v[42:43]
	v_pk_fma_f32 v[40:41], v[70:71], v[78:79], v[40:41]
	v_pk_fma_f32 v[38:39], v[72:73], v[84:85], v[38:39]
	v_pk_fma_f32 v[36:37], v[70:71], v[82:83], v[36:37]
	v_pk_fma_f32 v[34:35], v[72:73], v[88:89], v[34:35]
	v_pk_fma_f32 v[32:33], v[70:71], v[86:87], v[32:33]
	ds_write_b128 v65, v[44:47] offset:4096
	ds_write_b128 v65, v[40:43] offset:5120
	ds_write_b128 v65, v[36:39] offset:6144
	ds_write_b128 v65, v[32:35] offset:7168
	s_branch .LBB0_497
.Lmy_hlc_g2:
	ds_read_b128 v[66:69], v64 offset:11648
	ds_read_b128 v[70:73], v64 offset:11904
	ds_read_b128 v[74:77], v65 offset:8192
	ds_read_b128 v[78:81], v65 offset:9216
	ds_read_b128 v[82:85], v65 offset:10240
	ds_read_b128 v[86:89], v65 offset:11264
	s_waitcnt lgkmcnt(4)
	v_pk_mul_f32 v[72:73], v[68:69], v[72:73]
	v_pk_mul_f32 v[70:71], v[66:67], v[70:71]
	s_waitcnt lgkmcnt(0)
	v_pk_fma_f32 v[30:31], v[72:73], v[76:77], v[30:31]
	v_pk_fma_f32 v[28:29], v[70:71], v[74:75], v[28:29]
	v_pk_fma_f32 v[26:27], v[72:73], v[80:81], v[26:27]
	v_pk_fma_f32 v[24:25], v[70:71], v[78:79], v[24:25]
	v_pk_fma_f32 v[22:23], v[72:73], v[84:85], v[22:23]
	v_pk_fma_f32 v[20:21], v[70:71], v[82:83], v[20:21]
	v_pk_fma_f32 v[18:19], v[72:73], v[88:89], v[18:19]
	v_pk_fma_f32 v[16:17], v[70:71], v[86:87], v[16:17]
	ds_write_b128 v65, v[28:31] offset:8192
	ds_write_b128 v65, v[24:27] offset:9216
	ds_write_b128 v65, v[20:23] offset:10240
	ds_write_b128 v65, v[16:19] offset:11264
	s_branch .LBB0_497

; #define LAS __attribute__((address_space(3)))
; template <bool OUT> __device__ __forceinline__ void hgrn_item2(const PA& a, LAS unsigned char* lds, int layer, int bh, int c, int wave, int lane, const HRaw& raw) {
;     ...
; #pragma unroll 1
;     for (int step = 0; step < 8; ++step) {
;         if (wave == step) {
; #pragma unroll
;             for (int mt = 0; mt < 4; ++mt) { const f32x4 Dv = *(const LAS f32x4*)(DL + 16 * mt + 4 * q);
; #pragma unroll
;                 for (int nt = 0; nt < 4; ++nt) {
;                     Sp[mt][nt] = *(const LAS f32x4*)(SBUF + ((mt * 4 + nt) * 64 + lane) * 4);
;                     U[mt][nt] = Dv * Sp[mt][nt] + U[mt][nt];
;                     *(LAS f32x4*)(SBUF + ((mt * 4 + nt) * 64 + lane) * 4) = U[mt][nt];
;                 } }
;         }
;         __syncthreads();
;     }
.LBB0_729:
	s_add_i32 s13, s13, 1
	s_cmp_lg_u32 s13, 11
	s_waitcnt lgkmcnt(0)
	s_barrier
	s_cbranch_scc0 .LBB0_732
.LBB0_730:
	v_add_u32_e32 v227, 0x18000, v226
	v_add_u32_e32 v228, 0x18400, v226
	v_add_u32_e32 v229, 0x18800, v226
	v_add_u32_e32 v230, 0x18c00, v226
	v_add_u32_e32 v231, 0x19000, v226
	v_add_u32_e32 v232, 0x19400, v226
	v_add_u32_e32 v233, 0x19800, v226
	v_add_u32_e32 v242, 0x19c00, v226
	v_add_u32_e32 v243, 0x1a000, v226
	v_add_u32_e32 v244, 0x1a400, v226
	v_add_u32_e32 v245, 0x1a800, v226
	v_add_u32_e32 v246, 0x1ac00, v226
	v_add_u32_e32 v247, 0x1b000, v226
	v_add_u32_e32 v248, 0x1b400, v226
	v_add_u32_e32 v249, 0x1b800, v226
	v_add_u32_e32 v250, 0x1bc00, v226
	s_sub_i32 s0, s13, s2
	s_cmp_gt_u32 s0, 3
	s_cbranch_scc1 .LBB0_729
	s_cmp_eq_u32 s0, 0
	s_cbranch_scc1 .Lmy_c1_g0
	s_cmp_eq_u32 s0, 1
	s_cbranch_scc1 .Lmy_c1_g1
	s_cmp_eq_u32 s0, 2
	s_cbranch_scc1 .Lmy_c1_g2
	v_add_u32_e32 v148, s3, v208
	ds_read_b128 v[190:193], v148 offset:11712
	ds_read_b128 v[140:143], v247
	ds_read_b128 v[128:131], v248
	ds_read_b128 v[148:151], v249
	ds_read_b128 v[164:167], v250
	s_waitcnt lgkmcnt(0)
	v_pk_fma_f32 v[108:109], v[190:191], v[140:141], v[108:109]
	v_pk_fma_f32 v[110:111], v[192:193], v[142:143], v[110:111]
	v_pk_fma_f32 v[112:113], v[190:191], v[128:129], v[112:113]
	v_pk_fma_f32 v[114:115], v[192:193], v[130:131], v[114:115]
	v_pk_fma_f32 v[116:117], v[190:191], v[148:149], v[116:117]
	v_pk_fma_f32 v[118:119], v[192:193], v[150:151], v[118:119]
	v_pk_fma_f32 v[120:121], v[190:191], v[164:165], v[120:121]
	v_pk_fma_f32 v[122:123], v[192:193], v[166:167], v[122:123]
	ds_write_b128 v247, v[108:111]
	ds_write_b128 v248, v[112:115]
	ds_write_b128 v249, v[116:119]
	ds_write_b128 v250, v[120:123]
	s_branch .LBB0_729
.Lmy_c1_g0:
	v_add_u32_e32 v148, s3, v208
	ds_read_b128 v[128:131], v148 offset:11520
	ds_read_b128 v[136:139], v227
	ds_read_b128 v[152:155], v228
	ds_read_b128 v[168:171], v229
	ds_read_b128 v[180:183], v230
	s_waitcnt lgkmcnt(0)
	v_pk_fma_f32 v[56:57], v[128:129], v[136:137], v[56:57]
	v_pk_fma_f32 v[58:59], v[130:131], v[138:139], v[58:59]
	v_pk_fma_f32 v[60:61], v[128:129], v[152:153], v[60:61]
	v_pk_fma_f32 v[62:63], v[130:131], v[154:155], v[62:63]
	v_pk_fma_f32 v[64:65], v[128:129], v[168:169], v[64:65]
	v_pk_fma_f32 v[66:67], v[130:131], v[170:171], v[66:67]
	v_pk_fma_f32 v[68:69], v[128:129], v[180:181], v[68:69]
	v_pk_fma_f32 v[70:71], v[130:131], v[182:183], v[70:71]
	ds_write_b128 v227, v[56:59]
	ds_write_b128 v228, v[60:63]
	ds_write_b128 v229, v[64:67]
	ds_write_b128 v230, v[68:71]
	s_branch .LBB0_729
.Lmy_c1_g1:
	v_add_u32_e32 v148, s3, v208
	ds_read_b128 v[128:131], v148 offset:11584
	ds_read_b128 v[132:135], v231
	ds_read_b128 v[124:127], v232
	ds_read_b128 v[144:147], v233
	ds_read_b128 v[160:163], v242
	s_waitcnt lgkmcnt(0)
	v_pk_fma_f32 v[72:73], v[128:129], v[132:133], v[72:73]
	v_pk_fma_f32 v[74:75], v[130:131], v[134:135], v[74:75]
	v_pk_fma_f32 v[76:77], v[128:129], v[124:125], v[76:77]
	v_pk_fma_f32 v[78:79], v[130:131], v[126:127], v[78:79]
	v_pk_fma_f32 v[80:81], v[128:129], v[144:145], v[80:81]
	v_pk_fma_f32 v[82:83], v[130:131], v[146:147], v[82:83]
	v_pk_fma_f32 v[84:85], v[128:129], v[160:161], v[84:85]
	v_pk_fma_f32 v[86:87], v[130:131], v[162:163], v[86:87]
	ds_write_b128 v231, v[72:75]
	ds_write_b128 v232, v[76:79]
	ds_write_b128 v233, v[80:83]
	ds_write_b128 v242, v[84:87]
	s_branch .LBB0_729
.Lmy_c1_g2:
	v_add_u32_e32 v148, s3, v208
	ds_read_b128 v[140:143], v148 offset:11648
	ds_read_b128 v[156:159], v243
	ds_read_b128 v[172:175], v244
	ds_read_b128 v[176:179], v245
	ds_read_b128 v[184:187], v246
	s_waitcnt lgkmcnt(0)
	v_pk_fma_f32 v[88:89], v[140:141], v[156:157], v[88:89]
	v_pk_fma_f32 v[90:91], v[142:143], v[158:159], v[90:91]
	v_pk_fma_f32 v[92:93], v[140:141], v[172:173], v[92:93]
	v_pk_fma_f32 v[94:95], v[142:143], v[174:175], v[94:95]
	v_pk_fma_f32 v[96:97], v[140:141], v[176:177], v[96:97]
	v_pk_fma_f32 v[98:99], v[142:143], v[178:179], v[98:99]
	v_pk_fma_f32 v[100:101], v[140:141], v[184:185], v[100:101]
	v_pk_fma_f32 v[102:103], v[142:143], v[186:187], v[102:103]
	ds_write_b128 v243, v[88:91]
	ds_write_b128 v244, v[92:95]
	ds_write_b128 v245, v[96:99]
	ds_write_b128 v246, v[100:103]
	s_branch .LBB0_729

; #define LAS __attribute__((address_space(3)))
; template <bool OUT> __device__ __forceinline__ void hgrn_item2(const PA& a, LAS unsigned char* lds, int layer, int bh, int c, int wave, int lane, const HRaw& raw) {
;     ...
;     f32x4 Sp[4][4];
; #pragma unroll 1
;     for (int step = 0; step < 8; ++step) {
;         if (wave == step) {
; #pragma unroll
;             for (int mt = 0; mt < 4; ++mt) { const f32x4 Dv = *(const LAS f32x4*)(DL + 16 * mt + 4 * q);
; #pragma unroll
;                 for (int nt = 0; nt < 4; ++nt) {
;                     Sp[mt][nt] = *(const LAS f32x4*)(SBUF + ((mt * 4 + nt) * 64 + lane) * 4);
;                     U[mt][nt] = Dv * Sp[mt][nt] + U[mt][nt];
;                     *(LAS f32x4*)(SBUF + ((mt * 4 + nt) * 64 + lane) * 4) = U[mt][nt];
;                 } }
;         }
;         __syncthreads();
;     }
.LBB0_753:
	s_add_i32 s10, s10, 1
	s_cmp_lg_u32 s10, 11
	s_waitcnt lgkmcnt(0)
	s_barrier
	s_cbranch_scc0 .LBB0_707
.LBB0_754:
	s_sub_i32 s0, s10, s2
	s_cmp_gt_u32 s0, 3
	s_cbranch_scc1 .LBB0_753
	s_cmp_eq_u32 s0, 0
	s_cbranch_scc1 .Lmy_c2_g0
	s_cmp_eq_u32 s0, 1
	s_cbranch_scc1 .Lmy_c2_g1
	s_cmp_eq_u32 s0, 2
	s_cbranch_scc1 .Lmy_c2_g2
	ds_read_b128 v[160:163], v251 offset:11712
	ds_read_b128 v[108:111], v247
	ds_read_b128 v[96:99], v248
	ds_read_b128 v[116:119], v249
	ds_read_b128 v[132:135], v250
	s_waitcnt lgkmcnt(0)
	v_pk_fma_f32 v[76:77], v[160:161], v[108:109], v[76:77]
	v_pk_fma_f32 v[78:79], v[162:163], v[110:111], v[78:79]
	v_pk_fma_f32 v[80:81], v[160:161], v[96:97], v[80:81]
	v_pk_fma_f32 v[82:83], v[162:163], v[98:99], v[82:83]
	v_pk_fma_f32 v[84:85], v[160:161], v[116:117], v[84:85]
	v_pk_fma_f32 v[86:87], v[162:163], v[118:119], v[86:87]
	v_pk_fma_f32 v[88:89], v[160:161], v[132:133], v[88:89]
	v_pk_fma_f32 v[90:91], v[162:163], v[134:135], v[90:91]
	ds_write_b128 v247, v[76:79]
	ds_write_b128 v248, v[80:83]
	ds_write_b128 v249, v[84:87]
	ds_write_b128 v250, v[88:91]
	s_branch .LBB0_753
.Lmy_c2_g0:
	ds_read_b128 v[96:99], v251 offset:11520
	ds_read_b128 v[104:107], v227
	ds_read_b128 v[120:123], v228
	ds_read_b128 v[136:139], v229
	ds_read_b128 v[148:151], v230
	s_waitcnt lgkmcnt(0)
	v_pk_fma_f32 v[24:25], v[96:97], v[104:105], v[24:25]
	v_pk_fma_f32 v[26:27], v[98:99], v[106:107], v[26:27]
	v_pk_fma_f32 v[28:29], v[96:97], v[120:121], v[28:29]
	v_pk_fma_f32 v[30:31], v[98:99], v[122:123], v[30:31]
	v_pk_fma_f32 v[32:33], v[96:97], v[136:137], v[32:33]
	v_pk_fma_f32 v[34:35], v[98:99], v[138:139], v[34:35]
	v_pk_fma_f32 v[36:37], v[96:97], v[148:149], v[36:37]
	v_pk_fma_f32 v[38:39], v[98:99], v[150:151], v[38:39]
	ds_write_b128 v227, v[24:27]
	ds_write_b128 v228, v[28:31]
	ds_write_b128 v229, v[32:35]
	ds_write_b128 v230, v[36:39]
	s_branch .LBB0_753
.Lmy_c2_g1:
	ds_read_b128 v[96:99], v251 offset:11584
	ds_read_b128 v[100:103], v231
	ds_read_b128 v[92:95], v232
	ds_read_b128 v[112:115], v233
	ds_read_b128 v[128:131], v242
	s_waitcnt lgkmcnt(0)
	v_pk_fma_f32 v[40:41], v[96:97], v[100:101], v[40:41]
	v_pk_fma_f32 v[42:43], v[98:99], v[102:103], v[42:43]
	v_pk_fma_f32 v[44:45], v[96:97], v[92:93], v[44:45]
	v_pk_fma_f32 v[46:47], v[98:99], v[94:95], v[46:47]
	v_pk_fma_f32 v[48:49], v[96:97], v[112:113], v[48:49]
	v_pk_fma_f32 v[50:51], v[98:99], v[114:115], v[50:51]
	v_pk_fma_f32 v[52:53], v[96:97], v[128:129], v[52:53]
	v_pk_fma_f32 v[54:55], v[98:99], v[130:131], v[54:55]
	ds_write_b128 v231, v[40:43]
	ds_write_b128 v232, v[44:47]
	ds_write_b128 v233, v[48:51]
	ds_write_b128 v242, v[52:55]
	s_branch .LBB0_753
.Lmy_c2_g2:
	ds_read_b128 v[108:111], v251 offset:11648
	ds_read_b128 v[124:127], v243
	ds_read_b128 v[140:143], v244
	ds_read_b128 v[144:147], v245
	ds_read_b128 v[152:155], v246
	s_waitcnt lgkmcnt(0)
	v_pk_fma_f32 v[56:57], v[108:109], v[124:125], v[56:57]
	v_pk_fma_f32 v[58:59], v[110:111], v[126:127], v[58:59]
	v_pk_fma_f32 v[60:61], v[108:109], v[140:141], v[60:61]
	v_pk_fma_f32 v[62:63], v[110:111], v[142:143], v[62:63]
	v_pk_fma_f32 v[64:65], v[108:109], v[144:145], v[64:65]
	v_pk_fma_f32 v[66:67], v[110:111], v[146:147], v[66:67]
	v_pk_fma_f32 v[68:69], v[108:109], v[152:153], v[68:69]
	v_pk_fma_f32 v[70:71], v[110:111], v[154:155], v[70:71]
	ds_write_b128 v243, v[56:59]
	ds_write_b128 v244, v[60:63]
	ds_write_b128 v245, v[64:67]
	ds_write_b128 v246, v[68:71]
	s_branch .LBB0_753
